# P0 row phase: the f32 input rows are loaded with the nt (streaming) hint; each row is read once there
# speedup vs baseline: 1.0099x; 1.0062x over previous
; #define LAS __attribute__((address_space(3)))
; DI unsigned pk_bf16(float lo, float hi) { f32x2 v = {lo, hi}; bf16x2_t b = __builtin_convertvector(v, bf16x2_t); return __builtin_bit_cast(unsigned, b); }
; DI void p0_row(const Params& P, int row, const f32x4 (&v)[4], bf16_t* U, float* LOGF, const LAS f32x4* wf, int lane) {
;     float ss = 0.f;
; #pragma unroll
;     for (int jj = 0; jj < 4; ++jj) { ss += (v[jj].x * v[jj].x + v[jj].y * v[jj].y) + (v[jj].z * v[jj].z + v[jj].w * v[jj].w); }
;     const float rstd = 1.f / sqrtf(wave_sum(ss) * (1.f / DM) + RMS_EPS);
;     u32x2* uo = (u32x2*)(U + (size_t)row * DM) + lane;
;     float acc[8];
; #pragma unroll
;     for (int j = 0; j < 8; ++j) acc[j] = 0.f;
; #pragma unroll
;     for (int jj = 0; jj < 4; ++jj) { const f32x4 g0 = *((const f32x4*)P.norm_g + lane + 64 * jj); const f32x4 y = v[jj] * rstd * g0;
;         u32x2 w; w.x = pk_bf16(y.x, y.y); w.y = pk_bf16(y.z, y.w); uo[64 * jj] = w;
; __global__ void __launch_bounds__(512) fwd_kernel(Params P) {
;     ...
;         for (int row0 = 4 * gw; row0 < MT; row0 += 4 * NGW) {
;             f32x4 xv[4][4];
; #pragma unroll
;             for (int b = 0; b < 4; ++b)
; #pragma unroll
;                 for (int jj = 0; jj < 4; ++jj) xv[b][jj] = ((const f32x4*)(P.x + (size_t)(row0 + b) * DM) + lane)[64 * jj];
; #pragma unroll
;             for (int b = 0; b < 4; ++b) p0_row(P, row0 + b, xv[b], U, LOGF, wf, lane);
.LBB0_222:
	global_load_dwordx4 v[184:187], v[202:203], off nt
	global_load_dwordx4 v[188:191], v[202:203], off offset:1024 nt
	global_load_dwordx4 v[176:179], v[202:203], off offset:2048 nt
	global_load_dwordx4 v[180:183], v[202:203], off offset:3072 nt
	global_load_dwordx4 v[222:225], v[196:197], off
	s_waitcnt vmcnt(4)
	v_pk_mul_f32 v[128:129], v[186:187], v[186:187]
	v_pk_mul_f32 v[130:131], v[184:185], v[184:185]
	s_waitcnt vmcnt(3) lgkmcnt(7)
	v_pk_mul_f32 v[132:133], v[190:191], v[190:191]
	s_waitcnt lgkmcnt(6)
	v_pk_mul_f32 v[134:135], v[188:189], v[188:189]
	s_waitcnt lgkmcnt(2)
	v_pk_mov_b32 v[140:141], v[130:131], v[128:129] op_sel:[1,0]
	v_mov_b32_e32 v131, v129
	v_pk_mov_b32 v[128:129], v[134:135], v[132:133] op_sel:[1,0]
	v_mov_b32_e32 v135, v133
	s_waitcnt vmcnt(2)
	v_mul_f32_e32 v136, v177, v177
	s_waitcnt vmcnt(1)
	v_mul_f32_e32 v139, v182, v182
	v_mul_f32_e32 v138, v179, v179
	v_pk_add_f32 v[130:131], v[140:141], v[130:131]
	v_pk_add_f32 v[128:129], v[128:129], v[134:135]
	s_waitcnt lgkmcnt(1)
	v_mul_f32_e32 v142, v183, v183
	s_waitcnt lgkmcnt(0)
	v_mul_f32_e32 v143, v180, v180
	v_mul_f32_e32 v144, v181, v181
	v_pk_fma_f32 v[132:133], v[176:177], v[176:177], v[136:137] op_sel_hi:[1,1,0]
	v_pk_fma_f32 v[136:137], v[178:179], v[178:179], v[138:139] op_sel_hi:[1,1,0]
	v_pk_add_f32 v[130:131], v[130:131], v[130:131] op_sel:[0,1] op_sel_hi:[1,0]
	v_pk_add_f32 v[128:129], v[128:129], v[128:129] op_sel:[0,1] op_sel_hi:[1,0]
	v_mov_b32_e32 v133, v139
	v_mov_b32_e32 v137, v142
	v_mov_b32_e32 v131, v143
	v_mov_b32_e32 v129, v144
	v_pk_add_f32 v[132:133], v[132:133], v[136:137]
	v_pk_add_f32 v[128:129], v[130:131], v[128:129]
	s_nop 0
	v_pk_add_f32 v[128:129], v[128:129], v[132:133]
	s_nop 0
	v_add_f32_e32 v128, v128, v129
	ds_bpermute_b32 v129, v193, v128
	s_waitcnt lgkmcnt(0)
	v_add_f32_e32 v129, v128, v129
	ds_bpermute_b32 v130, v195, v129
	v_add_co_u32_e32 v128, vcc, 0x1000, v202
	s_mov_b64 s[0:1], vcc
	s_waitcnt lgkmcnt(0)
	v_add_f32_e32 v131, v129, v130
	ds_bpermute_b32 v132, v211, v131
	v_add_co_u32_e32 v130, vcc, 0x2000, v202
	s_mov_b64 s[22:23], vcc
	v_addc_co_u32_e64 v129, vcc, 0, v203, s[0:1]
	s_waitcnt lgkmcnt(0)
	v_add_f32_e32 v132, v131, v132
	ds_bpermute_b32 v133, v212, v132
	global_load_dwordx4 v[172:175], v[128:129], off nt
	global_load_dwordx4 v[168:171], v[128:129], off offset:1024 nt
	global_load_dwordx4 v[164:167], v[128:129], off offset:2048 nt
	global_load_dwordx4 v[160:163], v[128:129], off offset:3072 nt
	v_add_co_u32_e32 v206, vcc, 0x3000, v202
	v_addc_co_u32_e64 v131, s[0:1], 0, v203, s[22:23]
	s_waitcnt lgkmcnt(0)
	v_add_f32_e32 v132, v132, v133
	ds_bpermute_b32 v133, v213, v132
	v_addc_co_u32_e32 v207, vcc, 0, v203, vcc
	global_load_dwordx4 v[156:159], v[130:131], off nt
	global_load_dwordx4 v[152:155], v[130:131], off offset:1024 nt
	global_load_dwordx4 v[148:151], v[130:131], off offset:2048 nt
	global_load_dwordx4 v[144:147], v[130:131], off offset:3072 nt
	global_load_dwordx4 v[140:143], v[206:207], off nt
	global_load_dwordx4 v[136:139], v[206:207], off offset:1024 nt
	s_waitcnt lgkmcnt(0)
	v_add_f32_e32 v128, v132, v133
	ds_bpermute_b32 v129, v214, v128
	s_waitcnt lgkmcnt(0)
	v_add_f32_e32 v128, v128, v129
	v_fmamk_f32 v128, v128, 0x3a800000, v215
	v_mul_f32_e32 v129, 0x4f800000, v128
	v_cmp_gt_f32_e32 vcc, s3, v128
	s_nop 1
	v_cndmask_b32_e32 v128, v128, v129, vcc
	v_sqrt_f32_e32 v129, v128
	s_nop 0
	v_add_u32_e32 v130, -1, v129
	v_add_u32_e32 v131, 1, v129
	v_fma_f32 v132, -v130, v129, v128
	v_fma_f32 v133, -v131, v129, v128
	v_cmp_ge_f32_e64 s[0:1], 0, v132
	s_nop 1
	v_cndmask_b32_e64 v129, v129, v130, s[0:1]
	v_cmp_lt_f32_e64 s[0:1], 0, v133
	s_nop 1
	v_cndmask_b32_e64 v129, v129, v131, s[0:1]
	v_mul_f32_e32 v130, 0x37800000, v129
	v_cndmask_b32_e32 v129, v129, v130, vcc
	v_cmp_class_f32_e32 vcc, v128, v216
	s_nop 1
	v_cndmask_b32_e32 v205, v129, v128, vcc
	v_div_scale_f32 v208, s[0:1], v205, v205, 1.0
	v_rcp_f32_e32 v209, v208
	global_load_dwordx4 v[132:135], v[206:207], off offset:2048 nt
	global_load_dwordx4 v[128:131], v[206:207], off offset:3072 nt
	v_div_scale_f32 v206, vcc, 1.0, v205, 1.0
	v_fma_f32 v207, -v208, v209, 1.0
	v_fmac_f32_e32 v209, v207, v209
	v_mul_f32_e32 v207, v206, v209
	v_fma_f32 v210, -v208, v207, v206
	v_fmac_f32_e32 v207, v210, v209
	v_fma_f32 v206, -v208, v207, v206
	v_div_fmas_f32 v206, v206, v209, v207
	v_div_fixup_f32 v210, v206, v205, 1.0
	v_pk_mul_f32 v[184:185], v[184:185], v[210:211] op_sel_hi:[1,0]
	v_pk_mul_f32 v[186:187], v[186:187], v[210:211] op_sel_hi:[1,0]
	s_waitcnt vmcnt(12)
	v_pk_mul_f32 v[208:209], v[222:223], v[184:185]
	v_pk_mul_f32 v[206:207], v[224:225], v[186:187]
	v_cvt_pk_bf16_f32 v184, v208, v209
	v_cvt_pk_bf16_f32 v185, v206, v207
	global_store_dwordx2 v[200:201], v[184:185], off
	global_load_dwordx4 v[184:187], v[196:197], off offset:1024
	v_pk_mul_f32 v[222:223], v[188:189], v[210:211] op_sel_hi:[1,0]
	v_pk_mul_f32 v[188:189], v[190:191], v[210:211] op_sel_hi:[1,0]
	v_pk_mul_f32 v[176:177], v[176:177], v[210:211] op_sel_hi:[1,0]
	v_pk_mul_f32 v[178:179], v[178:179], v[210:211] op_sel_hi:[1,0]
	v_pk_mul_f32 v[180:181], v[180:181], v[210:211] op_sel_hi:[1,0]
	v_pk_mul_f32 v[182:183], v[182:183], v[210:211] op_sel_hi:[1,0]
	v_fma_f32 v205, v0, v208, 0
	v_fma_f32 v210, v1, v208, 0
	v_fma_f32 v221, v2, v208, 0
	v_fma_f32 v224, v5, v208, 0
	v_fma_f32 v225, v6, v208, 0
	v_fmac_f32_e32 v205, v8, v209
	v_fmac_f32_e32 v210, v9, v209
	v_fmac_f32_e32 v221, v10, v209
	v_fmac_f32_e32 v224, v13, v209
	v_fmac_f32_e32 v225, v14, v209
	v_fmac_f32_e32 v205, v16, v206
	v_fmac_f32_e32 v210, v17, v206
	v_fmac_f32_e32 v221, v18, v206
	v_fmac_f32_e32 v224, v21, v206
	v_fmac_f32_e32 v225, v22, v206
	v_fmac_f32_e32 v205, v24, v207
	v_fmac_f32_e32 v210, v25, v207
	v_fmac_f32_e32 v221, v26, v207
	v_fmac_f32_e32 v224, v29, v207
	v_fmac_f32_e32 v225, v30, v207
	s_ashr_i32 s0, s28, 11
	s_waitcnt vmcnt(0)
; DI unsigned pk_bf16(float lo, float hi) { f32x2 v = {lo, hi}; bf16x2_t b = __builtin_convertvector(v, bf16x2_t); return __builtin_bit_cast(unsigned, b); }
; DI void p0_row(const Params& P, int row, const f32x4 (&v)[4], bf16_t* U, float* LOGF, const LAS f32x4* wf, int lane) {
;     ...
;     for (int jj = 0; jj < 4; ++jj) { const f32x4 g0 = *((const f32x4*)P.norm_g + lane + 64 * jj); const f32x4 y = v[jj] * rstd * g0;
;         u32x2 w; w.x = pk_bf16(y.x, y.y); w.y = pk_bf16(y.z, y.w); uo[64 * jj] = w;
; #pragma unroll
;         for (int e = 0; e < 4; ++e) { const f32x4 wa = wf[((jj * 4 + e) * 2 + 0) * 64 + lane], wb = wf[((jj * 4 + e) * 2 + 1) * 64 + lane]; const float ye = y[e];
;             acc[0] += ye * wa.x; acc[1] += ye * wa.y; acc[2] += ye * wa.z; acc[3] += ye * wa.w; acc[4] += ye * wb.x; acc[5] += ye * wb.y; acc[6] += ye * wb.z; acc[7] += ye * wb.w; } }
;     float mine = 0.f;
; #pragma unroll
;     for (int j = 0; j < 8; ++j) { const float s = wave_sum(acc[j]); if (lane == j) mine = s; }
	v_pk_mul_f32 v[188:189], v[188:189], v[186:187]
	v_pk_mul_f32 v[190:191], v[222:223], v[184:185]
	v_cvt_pk_bf16_f32 v185, v188, v189
	v_cvt_pk_bf16_f32 v184, v190, v191
	global_store_dwordx2 v[200:201], v[184:185], off offset:512
	global_load_dwordx4 v[184:187], v[196:197], off offset:2048
	v_fma_f32 v222, v3, v208, 0
	v_fma_f32 v223, v4, v208, 0
	v_fma_f32 v208, v7, v208, 0
	v_fmac_f32_e32 v222, v11, v209
	v_fmac_f32_e32 v223, v12, v209
	v_fmac_f32_e32 v208, v15, v209
	v_fmac_f32_e32 v222, v19, v206
	v_fmac_f32_e32 v223, v20, v206
	v_fmac_f32_e32 v208, v23, v206
	v_fmac_f32_e32 v222, v27, v207
	v_fmac_f32_e32 v223, v28, v207
	v_fmac_f32_e32 v208, v31, v207
	v_fmac_f32_e32 v205, v190, v32
	v_fmac_f32_e32 v210, v190, v33
	v_fmac_f32_e32 v221, v190, v34
	v_fmac_f32_e32 v222, v190, v35
	v_fmac_f32_e32 v223, v190, v36
	v_fmac_f32_e32 v224, v190, v37
	v_fmac_f32_e32 v225, v190, v38
	v_fmac_f32_e32 v208, v190, v39
	v_fmac_f32_e32 v205, v191, v40
	v_fmac_f32_e32 v210, v191, v41
	v_fmac_f32_e32 v221, v191, v42
	v_fmac_f32_e32 v222, v191, v43
	v_fmac_f32_e32 v223, v191, v44
	v_fmac_f32_e32 v224, v191, v45
	v_fmac_f32_e32 v225, v191, v46
	v_fmac_f32_e32 v208, v191, v47
	v_fmac_f32_e32 v205, v188, v48
	v_fmac_f32_e32 v210, v188, v49
	v_fmac_f32_e32 v221, v188, v50
	v_fmac_f32_e32 v222, v188, v51
	v_fmac_f32_e32 v223, v188, v52
	v_fmac_f32_e32 v224, v188, v53
	v_fmac_f32_e32 v225, v188, v54
	v_fmac_f32_e32 v208, v188, v55
	v_fmac_f32_e32 v205, v189, v56
	v_fmac_f32_e32 v210, v189, v57
	v_fmac_f32_e32 v221, v189, v58
	v_fmac_f32_e32 v222, v189, v59
	v_fmac_f32_e32 v223, v189, v60
	v_fmac_f32_e32 v224, v189, v61
	v_fmac_f32_e32 v225, v189, v62
	v_fmac_f32_e32 v208, v189, v63
	s_waitcnt vmcnt(0)
	v_pk_mul_f32 v[186:187], v[178:179], v[186:187]
	v_pk_mul_f32 v[184:185], v[176:177], v[184:185]
	v_cvt_pk_bf16_f32 v177, v186, v187
	v_cvt_pk_bf16_f32 v176, v184, v185
	global_store_dwordx2 v[200:201], v[176:177], off offset:1024
	global_load_dwordx4 v[176:179], v[196:197], off offset:3072
	v_fmac_f32_e32 v205, v184, v64
	v_fmac_f32_e32 v210, v184, v65
	v_fmac_f32_e32 v221, v184, v66
	v_fmac_f32_e32 v222, v184, v67
	v_fmac_f32_e32 v223, v184, v68
	v_fmac_f32_e32 v224, v184, v69
	v_fmac_f32_e32 v225, v184, v70
	v_fmac_f32_e32 v208, v184, v71
	v_fmac_f32_e32 v205, v185, v72
	v_fmac_f32_e32 v210, v185, v73
	v_fmac_f32_e32 v221, v185, v74
	v_fmac_f32_e32 v222, v185, v75
	v_fmac_f32_e32 v223, v185, v76
	v_fmac_f32_e32 v224, v185, v77
	v_fmac_f32_e32 v225, v185, v78
	v_fmac_f32_e32 v208, v185, v79
	v_fmac_f32_e32 v205, v186, v80
	v_fmac_f32_e32 v210, v186, v81
	v_fmac_f32_e32 v221, v186, v82
	v_fmac_f32_e32 v222, v186, v83
	v_fmac_f32_e32 v223, v186, v84
	v_fmac_f32_e32 v224, v186, v85
	v_fmac_f32_e32 v225, v186, v86
	v_fmac_f32_e32 v208, v186, v87
	v_fmac_f32_e32 v205, v187, v88
	v_fmac_f32_e32 v210, v187, v89
	v_fmac_f32_e32 v221, v187, v90
	v_fmac_f32_e32 v222, v187, v91
	v_fmac_f32_e32 v223, v187, v92
	v_fmac_f32_e32 v224, v187, v93
	v_fmac_f32_e32 v225, v187, v94
	v_fmac_f32_e32 v208, v187, v95
	s_waitcnt vmcnt(0)
	v_pk_mul_f32 v[176:177], v[180:181], v[176:177]
	s_nop 0
	v_fmac_f32_e32 v205, v176, v96
	v_fmac_f32_e32 v210, v176, v97
	v_fmac_f32_e32 v221, v176, v98
	v_fmac_f32_e32 v222, v176, v99
	v_fmac_f32_e32 v223, v176, v100
	v_fmac_f32_e32 v224, v176, v101
	v_fmac_f32_e32 v225, v176, v102
	v_fmac_f32_e32 v208, v176, v103
	v_pk_mul_f32 v[178:179], v[182:183], v[178:179]
	v_fmac_f32_e32 v205, v177, v104
	v_fmac_f32_e32 v210, v177, v105
	v_fmac_f32_e32 v221, v177, v106
	v_fmac_f32_e32 v222, v177, v107
	v_fmac_f32_e32 v223, v177, v108
	v_fmac_f32_e32 v224, v177, v109
	v_fmac_f32_e32 v225, v177, v110
	v_fmac_f32_e32 v208, v177, v111
	v_fmac_f32_e32 v205, v178, v112
	v_fmac_f32_e32 v210, v178, v113
	v_fmac_f32_e32 v221, v178, v114
	v_fmac_f32_e32 v222, v178, v115
	v_fmac_f32_e32 v223, v178, v116
	v_fmac_f32_e32 v224, v178, v117
	v_fmac_f32_e32 v225, v178, v118
	v_fmac_f32_e32 v208, v178, v119
	v_cvt_pk_bf16_f32 v180, v176, v177
	v_cvt_pk_bf16_f32 v181, v178, v179
	v_fmac_f32_e32 v205, v179, v120
	v_fmac_f32_e32 v210, v179, v121
	v_fmac_f32_e32 v221, v179, v122
	v_fmac_f32_e32 v222, v179, v123
	v_fmac_f32_e32 v223, v179, v124
	v_fmac_f32_e32 v224, v179, v125
	v_fmac_f32_e32 v225, v179, v126
	v_fmac_f32_e32 v208, v179, v127
	global_store_dwordx2 v[200:201], v[180:181], off offset:1536
	ds_bpermute_b32 v176, v193, v205
	ds_bpermute_b32 v177, v193, v210
	ds_bpermute_b32 v178, v193, v221
	ds_bpermute_b32 v179, v193, v222
	ds_bpermute_b32 v180, v193, v223
	ds_bpermute_b32 v181, v193, v224
	ds_bpermute_b32 v182, v193, v225
	ds_bpermute_b32 v183, v193, v208
	s_waitcnt lgkmcnt(7)
	v_add_f32_e32 v176, v205, v176
	s_waitcnt lgkmcnt(6)
	v_add_f32_e32 v177, v210, v177
	s_waitcnt lgkmcnt(5)
	v_add_f32_e32 v178, v221, v178
	s_waitcnt lgkmcnt(4)
	v_add_f32_e32 v179, v222, v179
	s_waitcnt lgkmcnt(3)
	v_add_f32_e32 v180, v223, v180
	s_waitcnt lgkmcnt(2)
	v_add_f32_e32 v181, v224, v181
	s_waitcnt lgkmcnt(1)
	v_add_f32_e32 v182, v225, v182
	s_waitcnt lgkmcnt(0)
	v_add_f32_e32 v183, v208, v183
	ds_bpermute_b32 v184, v195, v176
	ds_bpermute_b32 v185, v195, v177
	ds_bpermute_b32 v186, v195, v178
	ds_bpermute_b32 v187, v195, v179
	ds_bpermute_b32 v188, v195, v180
	ds_bpermute_b32 v189, v195, v181
	ds_bpermute_b32 v190, v195, v182
	ds_bpermute_b32 v191, v195, v183
	s_waitcnt lgkmcnt(7)
	v_add_f32_e32 v176, v176, v184
	s_waitcnt lgkmcnt(6)
	v_add_f32_e32 v177, v177, v185
	s_waitcnt lgkmcnt(5)
	v_add_f32_e32 v178, v178, v186
	s_waitcnt lgkmcnt(4)
	v_add_f32_e32 v179, v179, v187
	s_waitcnt lgkmcnt(3)
	v_add_f32_e32 v180, v180, v188
	s_waitcnt lgkmcnt(2)
	v_add_f32_e32 v181, v181, v189
	s_waitcnt lgkmcnt(1)
; DI float log_sigmoid_f(float z) { return fminf(z, 0.f) - log1pf(__expf(-fabsf(z))); }
; DI float wave_sum(float v) {
;     ...
;     for (int o = 1; o < 64; o <<= 1) v += __shfl_xor(v, o);
; DI void p0_row(const Params& P, int row, const f32x4 (&v)[4], bf16_t* U, float* LOGF, const LAS f32x4* wf, int lane) {
;     ...
;     for (int j = 0; j < 8; ++j) { const float s = wave_sum(acc[j]); if (lane == j) mine = s; }
;     if (lane < 8) { const int b = row >> 14, t = row & (SEQ - 1); LOGF[(size_t)(b * 8 + lane) * SEQ + t] = log_sigmoid_f(mine + P.b_f[lane]); }
	v_add_f32_e32 v182, v182, v190
	s_waitcnt lgkmcnt(0)
	v_add_f32_e32 v183, v183, v191
	ds_bpermute_b32 v184, v211, v176
	ds_bpermute_b32 v185, v211, v177
	ds_bpermute_b32 v186, v211, v178
	ds_bpermute_b32 v187, v211, v179
	ds_bpermute_b32 v188, v211, v180
	ds_bpermute_b32 v189, v211, v181
	ds_bpermute_b32 v190, v211, v182
	ds_bpermute_b32 v191, v211, v183
	s_waitcnt lgkmcnt(7)
	v_add_f32_e32 v176, v176, v184
	s_waitcnt lgkmcnt(6)
	v_add_f32_e32 v177, v177, v185
	s_waitcnt lgkmcnt(5)
	v_add_f32_e32 v178, v178, v186
	s_waitcnt lgkmcnt(4)
	v_add_f32_e32 v179, v179, v187
	s_waitcnt lgkmcnt(3)
	v_add_f32_e32 v180, v180, v188
	s_waitcnt lgkmcnt(2)
	v_add_f32_e32 v181, v181, v189
	s_waitcnt lgkmcnt(1)
	v_add_f32_e32 v182, v182, v190
	s_waitcnt lgkmcnt(0)
	v_add_f32_e32 v183, v183, v191
	ds_bpermute_b32 v184, v212, v176
	ds_bpermute_b32 v185, v212, v177
	ds_bpermute_b32 v186, v212, v178
	ds_bpermute_b32 v187, v212, v179
	ds_bpermute_b32 v188, v212, v180
	ds_bpermute_b32 v189, v212, v181
	ds_bpermute_b32 v190, v212, v182
	ds_bpermute_b32 v191, v212, v183
	s_waitcnt lgkmcnt(7)
	v_add_f32_e32 v176, v176, v184
	s_waitcnt lgkmcnt(6)
	v_add_f32_e32 v177, v177, v185
	s_waitcnt lgkmcnt(5)
	v_add_f32_e32 v184, v178, v186
	s_waitcnt lgkmcnt(4)
	v_add_f32_e32 v185, v179, v187
	s_waitcnt lgkmcnt(3)
	v_add_f32_e32 v186, v180, v188
	s_waitcnt lgkmcnt(2)
	v_add_f32_e32 v187, v181, v189
	s_waitcnt lgkmcnt(1)
	v_add_f32_e32 v188, v182, v190
	s_waitcnt lgkmcnt(0)
	v_add_f32_e32 v189, v183, v191
	ds_bpermute_b32 v178, v213, v176
	ds_bpermute_b32 v179, v213, v177
	ds_bpermute_b32 v180, v213, v184
	ds_bpermute_b32 v181, v213, v185
	ds_bpermute_b32 v182, v213, v186
	ds_bpermute_b32 v183, v213, v187
	ds_bpermute_b32 v190, v213, v188
	ds_bpermute_b32 v191, v213, v189
	s_waitcnt lgkmcnt(7)
	v_add_f32_e32 v178, v176, v178
	s_waitcnt lgkmcnt(6)
	v_add_f32_e32 v179, v177, v179
	s_waitcnt lgkmcnt(5)
	v_add_f32_e32 v180, v184, v180
	s_waitcnt lgkmcnt(4)
	v_add_f32_e32 v181, v185, v181
	s_waitcnt lgkmcnt(3)
	v_add_f32_e32 v182, v186, v182
	s_waitcnt lgkmcnt(2)
	v_add_f32_e32 v183, v187, v183
	s_waitcnt lgkmcnt(1)
	v_add_f32_e32 v185, v188, v190
	s_waitcnt lgkmcnt(0)
	v_add_f32_e32 v187, v189, v191
	ds_bpermute_b32 v184, v214, v178
	ds_bpermute_b32 v186, v214, v179
	ds_bpermute_b32 v188, v214, v180
	ds_bpermute_b32 v189, v214, v181
	ds_bpermute_b32 v190, v214, v182
	ds_bpermute_b32 v191, v214, v183
	ds_bpermute_b32 v205, v214, v185
	ds_bpermute_b32 v206, v214, v187
	v_and_or_b32 v176, s0, -8, v192
	v_ashrrev_i32_e32 v177, 31, v176
	v_lshlrev_b64 v[176:177], 16, v[176:177]
	v_lshl_add_u64 v[176:177], s[26:27], 0, v[176:177]
	s_and_saveexec_b64 s[0:1], s[4:5]
	s_cbranch_execz .LBB0_224
; DI float log_sigmoid_f(float z) { return fminf(z, 0.f) - log1pf(__expf(-fabsf(z))); }
; DI void p0_row(const Params& P, int row, const f32x4 (&v)[4], bf16_t* U, float* LOGF, const LAS f32x4* wf, int lane) {
;     ...
;     for (int j = 0; j < 8; ++j) { const float s = wave_sum(acc[j]); if (lane == j) mine = s; }
;     if (lane < 8) { const int b = row >> 14, t = row & (SEQ - 1); LOGF[(size_t)(b * 8 + lane) * SEQ + t] = log_sigmoid_f(mine + P.b_f[lane]); }
	global_load_dword v207, v[198:199], off
	s_waitcnt lgkmcnt(7)
	v_add_f32_e32 v178, v178, v184
	s_waitcnt lgkmcnt(6)
	v_add_f32_e32 v179, v179, v186
	v_cndmask_b32_e64 v178, 0, v178, s[20:21]
	s_waitcnt lgkmcnt(5)
	v_add_f32_e32 v180, v180, v188
	v_cndmask_b32_e64 v178, v178, v179, s[18:19]
	s_waitcnt lgkmcnt(4)
	v_add_f32_e32 v181, v181, v189
	v_cndmask_b32_e64 v178, v178, v180, s[16:17]
	s_waitcnt lgkmcnt(3)
	v_add_f32_e32 v182, v182, v190
	v_cndmask_b32_e64 v178, v178, v181, s[14:15]
	s_waitcnt lgkmcnt(2)
	v_add_f32_e32 v183, v183, v191
	v_cndmask_b32_e64 v178, v178, v182, s[12:13]
	s_waitcnt lgkmcnt(1)
	v_add_f32_e32 v185, v185, v205
	v_cndmask_b32_e64 v178, v178, v183, s[10:11]
	s_waitcnt lgkmcnt(0)
	v_add_f32_e32 v187, v187, v206
	v_cndmask_b32_e64 v178, v178, v185, s[8:9]
	v_cndmask_b32_e64 v178, v178, v187, s[6:7]
	s_and_b32 s22, s28, 0x3ffc
	s_lshl_b32 s44, s22, 2
	s_waitcnt vmcnt(0)
	v_add_f32_e32 v178, v178, v207
	v_mul_f32_e64 v179, |v178|, s29
	v_exp_f32_e32 v206, v179
	v_min_f32_e32 v207, 0, v178
	v_add_f32_e32 v180, 1.0, v206
	v_add_f32_e32 v181, -1.0, v180
	v_frexp_mant_f32_e32 v182, v180
	v_cvt_f64_f32_e32 v[178:179], v180
	v_sub_f32_e32 v183, v181, v180
	v_frexp_exp_i32_f64_e32 v178, v[178:179]
	v_cmp_gt_f32_e32 vcc, s43, v182
	v_sub_f32_e32 v181, v206, v181
	v_add_f32_e32 v179, 1.0, v183
	v_subbrev_co_u32_e32 v178, vcc, 0, v178, vcc
	v_add_f32_e32 v179, v181, v179
	v_sub_u32_e32 v181, 0, v178
	v_ldexp_f32 v180, v180, v181
	v_add_f32_e32 v182, -1.0, v180
	v_add_f32_e32 v183, 1.0, v180
	v_ldexp_f32 v179, v179, v181
	v_add_f32_e32 v181, 1.0, v182
	v_add_f32_e32 v184, -1.0, v183
	v_sub_f32_e32 v181, v180, v181
	v_sub_f32_e32 v180, v180, v184
	v_add_f32_e32 v184, v179, v181
	v_add_f32_e32 v179, v179, v180
	v_add_f32_e32 v186, v183, v179
	v_rcp_f32_e32 v187, v186
	v_add_f32_e32 v181, v182, v184
	v_sub_f32_e32 v182, v181, v182
	v_sub_f32_e32 v180, v186, v183
	v_mul_f32_e32 v189, v181, v187
	v_sub_f32_e32 v188, v184, v182
	v_mul_f32_e32 v182, v186, v189
	v_sub_f32_e32 v179, v179, v180
	v_fma_f32 v184, v189, v186, -v182
	v_fmac_f32_e32 v184, v189, v179
	v_add_f32_e32 v180, v182, v184
	v_sub_f32_e32 v183, v181, v180
	v_mov_b32_e32 v185, v180
	v_pk_add_f32 v[180:181], v[180:181], v[182:183] neg_lo:[0,1] neg_hi:[0,1]
	v_cvt_f32_i32_e32 v178, v178
	v_pk_add_f32 v[180:181], v[180:181], v[184:185] neg_lo:[0,1] neg_hi:[0,1]
	v_cmp_neq_f32_e32 vcc, s53, v206
	v_add_f32_e32 v181, v188, v181
	v_add_f32_e32 v180, v180, v181
	v_add_f32_e32 v181, v183, v180
	v_mul_f32_e32 v185, v187, v181
	v_mul_f32_e32 v182, v186, v185
	v_sub_f32_e32 v183, v183, v181
	v_add_f32_e32 v190, v189, v185
	v_fma_f32 v184, v185, v186, -v182
	v_add_f32_e32 v188, v180, v183
	v_sub_f32_e32 v180, v190, v189
	v_fmac_f32_e32 v184, v185, v179
	v_sub_f32_e32 v179, v185, v180
	v_add_f32_e32 v180, v182, v184
	v_sub_f32_e32 v183, v181, v180
	v_mov_b32_e32 v185, v180
	v_pk_add_f32 v[180:181], v[180:181], v[182:183] neg_lo:[0,1] neg_hi:[0,1]
	s_nop 0
	v_pk_add_f32 v[180:181], v[180:181], v[184:185] neg_lo:[0,1] neg_hi:[0,1]
	s_nop 0
	v_add_f32_e32 v181, v188, v181
	v_add_f32_e32 v180, v180, v181
	v_add_f32_e32 v180, v183, v180
	v_mul_f32_e32 v180, v187, v180
	v_add_f32_e32 v179, v179, v180
	v_add_f32_e32 v180, v190, v179
	v_mul_f32_e32 v182, v180, v180
	v_sub_f32_e32 v183, v180, v190
	v_fmamk_f32 v184, v182, 0x3e9b6dac, v217
	v_sub_f32_e32 v183, v179, v183
	v_mul_f32_e32 v179, v180, v182
	v_fmaak_f32 v205, v182, v184, 0x3f2aaada
	v_ldexp_f32 v185, v183, 1
	v_pk_mul_f32 v[182:183], v[178:179], v[204:205]
	v_ldexp_f32 v181, v180, 1
	v_fma_f32 v180, v178, s52, -v182
	v_fmac_f32_e32 v180, 0xb102e308, v178
	v_pk_add_f32 v[178:179], v[182:183], v[180:181]
	v_mov_b32_e32 v184, v182
	v_sub_f32_e32 v188, v179, v181
	v_pk_add_f32 v[186:187], v[178:179], v[182:183] neg_lo:[0,1] neg_hi:[0,1]
	v_sub_f32_e32 v182, v183, v188
	v_add_f32_e32 v185, v185, v182
	v_pk_add_f32 v[182:183], v[178:179], v[184:185]
	v_mov_b32_e32 v181, v178
	v_mov_b32_e32 v187, v183
	v_pk_add_f32 v[190:191], v[180:181], v[186:187] neg_lo:[0,1] neg_hi:[0,1]
	v_pk_add_f32 v[180:181], v[180:181], v[186:187]
	v_mov_b32_e32 v189, v178
	v_pk_add_f32 v[186:187], v[180:181], v[178:179] op_sel:[1,0] op_sel_hi:[0,1] neg_lo:[0,1] neg_hi:[0,1]
	v_mov_b32_e32 v188, v185
	v_mov_b32_e32 v184, v183
	v_mov_b32_e32 v185, v181
	v_pk_mov_b32 v[178:179], v[178:179], v[186:187] op_sel:[1,0]
	v_pk_add_f32 v[182:183], v[182:183], v[186:187] op_sel_hi:[1,0] neg_lo:[0,1] neg_hi:[0,1]
	v_pk_add_f32 v[178:179], v[184:185], v[178:179] neg_lo:[0,1] neg_hi:[0,1]
	v_mov_b32_e32 v182, v190
	v_pk_add_f32 v[178:179], v[188:189], v[178:179] neg_lo:[0,1] neg_hi:[0,1]
	v_mov_b32_e32 v191, v181
	v_pk_add_f32 v[182:183], v[182:183], v[178:179]
	s_nop 0
	v_pk_add_f32 v[184:185], v[182:183], v[182:183] op_sel:[0,1] op_sel_hi:[1,0]
	s_nop 0
	v_pk_add_f32 v[180:181], v[180:181], v[184:185] op_sel:[1,0] op_sel_hi:[0,1]
	v_mov_b32_e32 v183, v180
	v_mov_b32_e32 v179, v184
	v_pk_add_f32 v[184:185], v[182:183], v[190:191] neg_lo:[0,1] neg_hi:[0,1]
	s_nop 0
	v_sub_f32_e32 v181, v182, v184
	v_pk_add_f32 v[178:179], v[178:179], v[184:185] neg_lo:[0,1] neg_hi:[0,1]
	v_sub_f32_e32 v181, v190, v181
	v_add_f32_e32 v178, v178, v181
	v_add_f32_e32 v178, v178, v179
	v_add_f32_e32 v178, v180, v178
	v_cndmask_b32_e32 v178, v218, v178, vcc
	v_cmp_ngt_f32_e32 vcc, -1.0, v206
	s_nop 1
	v_cndmask_b32_e32 v178, v219, v178, vcc
	v_cmp_neq_f32_e32 vcc, -1.0, v206
	s_nop 1
	v_cndmask_b32_e32 v178, v220, v178, vcc
	v_cmp_lt_f32_e64 vcc, |v206|, s54
	s_nop 1
	v_cndmask_b32_e32 v178, v178, v206, vcc
	v_sub_f32_e32 v180, v207, v178
	v_lshl_add_u64 v[178:179], v[176:177], 0, s[44:45]
	global_store_dword v[178:179], v180, off
